# weight-conversion tile loads: 8 loads in flight before one wait (three of four instances)
# speedup vs baseline: 1.0121x; 1.0121x over previous
; DEVI bf16_t f2bf(float f) { return (bf16_t)(cvt_pk_bf16(f, 0.f) & 0xffffu); }
; DEVI void ph_convert(const int wv, const Params& p, int l, unsigned char* lds, int mode  , int blk_lo) {
;     ...
;             const int nkt = K / 64, k0 = (t % nkt) * 64, n0 = (t / nkt) * 64;
;             for (int e = tid; e < 4096; e += NTHREADS) { const int kk = e >> 6, nn = e & 63; tile[kk * 65 + nn] = src[(size_t)(k0 + kk) * N + n0 + nn]; }
;             __syncthreads();
;             for (int e = tid; e < 4096; e += NTHREADS) { const int nn = e >> 6, kk = e & 63; dst[(size_t)(n0 + nn) * K + k0 + kk] = f2bf(tile[kk * 65 + nn]); }
.LBB0_175:
	v_ashrrev_i32_e32 v18, 6, v10
	v_ashrrev_i32_e32 v19, 6, v11
	v_add_u32_e32 v16, s28, v18
	v_add_u32_e32 v14, s13, v19
	v_ashrrev_i32_e32 v20, 31, v16
	v_ashrrev_i32_e32 v21, 31, v14
	v_mul_lo_u32 v23, s9, v16
	v_mad_u64_u32 v[16:17], s[40:41], s8, v16, 0
	v_mul_lo_u32 v20, s8, v20
	v_mul_lo_u32 v22, s39, v14
	v_mad_u64_u32 v[14:15], s[40:41], s29, v14, 0
	v_mul_lo_u32 v21, s29, v21
	v_add3_u32 v17, v17, v20, v23
	v_add3_u32 v15, v15, v21, v22
	v_lshl_add_u64 v[16:17], v[16:17], 2, v[8:9]
	v_lshl_add_u64 v[14:15], v[14:15], 2, v[8:9]
	global_load_dword v100, v[16:17], off
	global_load_dword v101, v[14:15], off
	v_add_u32_e32 v11, 0x400, v11
	v_add_u32_e32 v10, 0x400, v10
	v_mad_u64_u32 v[108:109], s[40:41], v18, s44, v[4:5]
	v_mad_u64_u32 v[110:111], s[40:41], v19, s44, v[4:5]
	v_ashrrev_i32_e32 v18, 6, v10
	v_ashrrev_i32_e32 v19, 6, v11
	v_add_u32_e32 v16, s28, v18
	v_add_u32_e32 v14, s13, v19
	v_ashrrev_i32_e32 v20, 31, v16
	v_ashrrev_i32_e32 v21, 31, v14
	v_mul_lo_u32 v23, s9, v16
	v_mad_u64_u32 v[16:17], s[40:41], s8, v16, 0
	v_mul_lo_u32 v20, s8, v20
	v_mul_lo_u32 v22, s39, v14
	v_mad_u64_u32 v[14:15], s[40:41], s29, v14, 0
	v_mul_lo_u32 v21, s29, v21
	v_add3_u32 v17, v17, v20, v23
	v_add3_u32 v15, v15, v21, v22
	v_lshl_add_u64 v[16:17], v[16:17], 2, v[8:9]
	v_lshl_add_u64 v[14:15], v[14:15], 2, v[8:9]
	global_load_dword v102, v[16:17], off
	global_load_dword v103, v[14:15], off
	v_add_u32_e32 v11, 0x400, v11
	v_add_u32_e32 v10, 0x400, v10
	v_mad_u64_u32 v[112:113], s[40:41], v18, s44, v[4:5]
	v_mad_u64_u32 v[114:115], s[40:41], v19, s44, v[4:5]
	v_ashrrev_i32_e32 v18, 6, v10
	v_ashrrev_i32_e32 v19, 6, v11
	v_add_u32_e32 v16, s28, v18
	v_add_u32_e32 v14, s13, v19
	v_ashrrev_i32_e32 v20, 31, v16
	v_ashrrev_i32_e32 v21, 31, v14
	v_mul_lo_u32 v23, s9, v16
	v_mad_u64_u32 v[16:17], s[40:41], s8, v16, 0
	v_mul_lo_u32 v20, s8, v20
	v_mul_lo_u32 v22, s39, v14
	v_mad_u64_u32 v[14:15], s[40:41], s29, v14, 0
	v_mul_lo_u32 v21, s29, v21
	v_add3_u32 v17, v17, v20, v23
	v_add3_u32 v15, v15, v21, v22
	v_lshl_add_u64 v[16:17], v[16:17], 2, v[8:9]
	v_lshl_add_u64 v[14:15], v[14:15], 2, v[8:9]
	global_load_dword v104, v[16:17], off
	global_load_dword v105, v[14:15], off
	v_add_u32_e32 v11, 0x400, v11
	v_add_u32_e32 v10, 0x400, v10
	v_mad_u64_u32 v[116:117], s[40:41], v18, s44, v[4:5]
	v_mad_u64_u32 v[118:119], s[40:41], v19, s44, v[4:5]
	v_ashrrev_i32_e32 v18, 6, v10
	v_ashrrev_i32_e32 v19, 6, v11
	v_add_u32_e32 v16, s28, v18
	v_add_u32_e32 v14, s13, v19
	v_ashrrev_i32_e32 v20, 31, v16
	v_ashrrev_i32_e32 v21, 31, v14
	v_mul_lo_u32 v23, s9, v16
	v_mad_u64_u32 v[16:17], s[40:41], s8, v16, 0
	v_mul_lo_u32 v20, s8, v20
	v_mul_lo_u32 v22, s39, v14
	v_mad_u64_u32 v[14:15], s[40:41], s29, v14, 0
	v_mul_lo_u32 v21, s29, v21
	v_add3_u32 v17, v17, v20, v23
	v_add3_u32 v15, v15, v21, v22
	v_lshl_add_u64 v[16:17], v[16:17], 2, v[8:9]
	v_lshl_add_u64 v[14:15], v[14:15], 2, v[8:9]
	global_load_dword v106, v[16:17], off
	global_load_dword v107, v[14:15], off
	v_add_u32_e32 v11, 0x400, v11
	v_add_u32_e32 v10, 0x400, v10
	v_mad_u64_u32 v[120:121], s[40:41], v18, s44, v[4:5]
	v_mad_u64_u32 v[122:123], s[40:41], v19, s44, v[4:5]
	s_waitcnt vmcnt(0)
	ds_write_b32 v108, v100
	ds_write_b32 v110, v101
	ds_write_b32 v112, v102
	ds_write_b32 v114, v103
	ds_write_b32 v116, v104
	ds_write_b32 v118, v105
	ds_write_b32 v120, v106
	ds_write_b32 v122, v107
	s_or_b64 exec, exec, s[36:37]
	s_orn2_b64 s[36:37], s[4:5], exec
	v_mov_b32_e32 v7, v13

; DEVI bf16_t f2bf(float f) { return (bf16_t)(cvt_pk_bf16(f, 0.f) & 0xffffu); }
; DEVI void ph_convert(const int wv, const Params& p, int l, unsigned char* lds, int mode  , int blk_lo) {
;     ...
;             const int nkt = K / 64, k0 = (t % nkt) * 64, n0 = (t / nkt) * 64;
;             for (int e = tid; e < 4096; e += NTHREADS) { const int kk = e >> 6, nn = e & 63; tile[kk * 65 + nn] = src[(size_t)(k0 + kk) * N + n0 + nn]; }
;             __syncthreads();
;             for (int e = tid; e < 4096; e += NTHREADS) { const int nn = e >> 6, kk = e & 63; dst[(size_t)(n0 + nn) * K + k0 + kk] = f2bf(tile[kk * 65 + nn]); }
.LBB0_313:
	v_ashrrev_i32_e32 v18, 6, v11
	v_ashrrev_i32_e32 v13, 6, v10
	v_add_u32_e32 v14, s11, v18
	v_add_u32_e32 v16, s12, v13
	v_ashrrev_i32_e32 v15, 31, v14
	v_ashrrev_i32_e32 v17, 31, v16
	v_mul_lo_u32 v19, s13, v15
	v_mul_lo_u32 v20, s18, v14
	v_mad_u64_u32 v[14:15], s[40:41], s13, v14, 0
	v_add3_u32 v15, v15, v19, v20
	v_mul_lo_u32 v19, s8, v17
	v_mul_lo_u32 v20, s9, v16
	v_mad_u64_u32 v[16:17], s[40:41], s8, v16, 0
	v_add3_u32 v17, v17, v19, v20
	v_lshl_add_u64 v[16:17], v[16:17], 2, v[8:9]
	v_lshl_add_u64 v[14:15], v[14:15], 2, v[8:9]
	global_load_dword v100, v[16:17], off
	global_load_dword v101, v[14:15], off
	v_mad_u64_u32 v[108:109], s[40:41], v13, s44, v[6:7]
	v_add_u32_e32 v11, 0x400, v11
	v_add_u32_e32 v10, 0x400, v10
	v_mad_u64_u32 v[110:111], s[40:41], v18, s44, v[6:7]
	v_ashrrev_i32_e32 v18, 6, v11
	v_ashrrev_i32_e32 v13, 6, v10
	v_add_u32_e32 v14, s11, v18
	v_add_u32_e32 v16, s12, v13
	v_ashrrev_i32_e32 v15, 31, v14
	v_ashrrev_i32_e32 v17, 31, v16
	v_mul_lo_u32 v19, s13, v15
	v_mul_lo_u32 v20, s18, v14
	v_mad_u64_u32 v[14:15], s[40:41], s13, v14, 0
	v_add3_u32 v15, v15, v19, v20
	v_mul_lo_u32 v19, s8, v17
	v_mul_lo_u32 v20, s9, v16
	v_mad_u64_u32 v[16:17], s[40:41], s8, v16, 0
	v_add3_u32 v17, v17, v19, v20
	v_lshl_add_u64 v[16:17], v[16:17], 2, v[8:9]
	v_lshl_add_u64 v[14:15], v[14:15], 2, v[8:9]
	global_load_dword v102, v[16:17], off
	global_load_dword v103, v[14:15], off
	v_mad_u64_u32 v[112:113], s[40:41], v13, s44, v[6:7]
	v_add_u32_e32 v11, 0x400, v11
	v_add_u32_e32 v10, 0x400, v10
	v_mad_u64_u32 v[114:115], s[40:41], v18, s44, v[6:7]
	v_ashrrev_i32_e32 v18, 6, v11
	v_ashrrev_i32_e32 v13, 6, v10
	v_add_u32_e32 v14, s11, v18
	v_add_u32_e32 v16, s12, v13
	v_ashrrev_i32_e32 v15, 31, v14
	v_ashrrev_i32_e32 v17, 31, v16
	v_mul_lo_u32 v19, s13, v15
	v_mul_lo_u32 v20, s18, v14
	v_mad_u64_u32 v[14:15], s[40:41], s13, v14, 0
	v_add3_u32 v15, v15, v19, v20
	v_mul_lo_u32 v19, s8, v17
	v_mul_lo_u32 v20, s9, v16
	v_mad_u64_u32 v[16:17], s[40:41], s8, v16, 0
	v_add3_u32 v17, v17, v19, v20
	v_lshl_add_u64 v[16:17], v[16:17], 2, v[8:9]
	v_lshl_add_u64 v[14:15], v[14:15], 2, v[8:9]
	global_load_dword v104, v[16:17], off
	global_load_dword v105, v[14:15], off
	v_mad_u64_u32 v[116:117], s[40:41], v13, s44, v[6:7]
	v_add_u32_e32 v11, 0x400, v11
	v_add_u32_e32 v10, 0x400, v10
	v_mad_u64_u32 v[118:119], s[40:41], v18, s44, v[6:7]
	v_ashrrev_i32_e32 v18, 6, v11
	v_ashrrev_i32_e32 v13, 6, v10
	v_add_u32_e32 v14, s11, v18
	v_add_u32_e32 v16, s12, v13
	v_ashrrev_i32_e32 v15, 31, v14
	v_ashrrev_i32_e32 v17, 31, v16
	v_mul_lo_u32 v19, s13, v15
	v_mul_lo_u32 v20, s18, v14
	v_mad_u64_u32 v[14:15], s[40:41], s13, v14, 0
	v_add3_u32 v15, v15, v19, v20
	v_mul_lo_u32 v19, s8, v17
	v_mul_lo_u32 v20, s9, v16
	v_mad_u64_u32 v[16:17], s[40:41], s8, v16, 0
	v_add3_u32 v17, v17, v19, v20
	v_lshl_add_u64 v[16:17], v[16:17], 2, v[8:9]
	v_lshl_add_u64 v[14:15], v[14:15], 2, v[8:9]
	global_load_dword v106, v[16:17], off
	global_load_dword v107, v[14:15], off
	v_mad_u64_u32 v[120:121], s[40:41], v13, s44, v[6:7]
	v_add_u32_e32 v11, 0x400, v11
	v_add_u32_e32 v10, 0x400, v10
	v_mad_u64_u32 v[122:123], s[40:41], v18, s44, v[6:7]
	s_waitcnt vmcnt(0)
	ds_write_b32 v108, v100
	ds_write_b32 v110, v101
	ds_write_b32 v112, v102
	ds_write_b32 v114, v103
	ds_write_b32 v116, v104
	ds_write_b32 v118, v105
	ds_write_b32 v120, v106
	ds_write_b32 v122, v107
	s_or_b64 exec, exec, s[36:37]
	s_orn2_b64 s[36:37], s[4:5], exec
	v_mov_b32_e32 v0, v12

; DEVI bf16_t f2bf(float f) { return (bf16_t)(cvt_pk_bf16(f, 0.f) & 0xffffu); }
; DEVI void ph_convert(const int wv, const Params& p, int l, unsigned char* lds, int mode  , int blk_lo) {
;     ...
;             const int nkt = K / 64, k0 = (t % nkt) * 64, n0 = (t / nkt) * 64;
;             for (int e = tid; e < 4096; e += NTHREADS) { const int kk = e >> 6, nn = e & 63; tile[kk * 65 + nn] = src[(size_t)(k0 + kk) * N + n0 + nn]; }
;             __syncthreads();
;             for (int e = tid; e < 4096; e += NTHREADS) { const int nn = e >> 6, kk = e & 63; dst[(size_t)(n0 + nn) * K + k0 + kk] = f2bf(tile[kk * 65 + nn]); }
.LBB0_1390:
	v_ashrrev_i32_e32 v23, 6, v17
	v_ashrrev_i32_e32 v22, 6, v16
	v_add_u32_e32 v18, s11, v23
	v_add_u32_e32 v20, s12, v22
	v_ashrrev_i32_e32 v19, 31, v18
	v_ashrrev_i32_e32 v21, 31, v20
	v_mul_lo_u32 v24, s13, v19
	v_mul_lo_u32 v25, s37, v18
	v_mad_u64_u32 v[18:19], s[38:39], s13, v18, 0
	v_add3_u32 v19, v19, v24, v25
	v_mul_lo_u32 v24, s8, v21
	v_mul_lo_u32 v25, s9, v20
	v_mad_u64_u32 v[20:21], s[38:39], s8, v20, 0
	v_add3_u32 v21, v21, v24, v25
	v_lshl_add_u64 v[20:21], v[20:21], 2, v[14:15]
	v_lshl_add_u64 v[18:19], v[18:19], 2, v[14:15]
	global_load_dword v100, v[20:21], off
	global_load_dword v101, v[18:19], off
	v_mad_u64_u32 v[108:109], s[38:39], v22, s44, v[8:9]
	v_add_u32_e32 v17, 0x400, v17
	v_add_u32_e32 v16, 0x400, v16
	v_mad_u64_u32 v[110:111], s[38:39], v23, s44, v[8:9]
	v_ashrrev_i32_e32 v23, 6, v17
	v_ashrrev_i32_e32 v22, 6, v16
	v_add_u32_e32 v18, s11, v23
	v_add_u32_e32 v20, s12, v22
	v_ashrrev_i32_e32 v19, 31, v18
	v_ashrrev_i32_e32 v21, 31, v20
	v_mul_lo_u32 v24, s13, v19
	v_mul_lo_u32 v25, s37, v18
	v_mad_u64_u32 v[18:19], s[38:39], s13, v18, 0
	v_add3_u32 v19, v19, v24, v25
	v_mul_lo_u32 v24, s8, v21
	v_mul_lo_u32 v25, s9, v20
	v_mad_u64_u32 v[20:21], s[38:39], s8, v20, 0
	v_add3_u32 v21, v21, v24, v25
	v_lshl_add_u64 v[20:21], v[20:21], 2, v[14:15]
	v_lshl_add_u64 v[18:19], v[18:19], 2, v[14:15]
	global_load_dword v102, v[20:21], off
	global_load_dword v103, v[18:19], off
	v_mad_u64_u32 v[112:113], s[38:39], v22, s44, v[8:9]
	v_add_u32_e32 v17, 0x400, v17
	v_add_u32_e32 v16, 0x400, v16
	v_mad_u64_u32 v[114:115], s[38:39], v23, s44, v[8:9]
	v_ashrrev_i32_e32 v23, 6, v17
	v_ashrrev_i32_e32 v22, 6, v16
	v_add_u32_e32 v18, s11, v23
	v_add_u32_e32 v20, s12, v22
	v_ashrrev_i32_e32 v19, 31, v18
	v_ashrrev_i32_e32 v21, 31, v20
	v_mul_lo_u32 v24, s13, v19
	v_mul_lo_u32 v25, s37, v18
	v_mad_u64_u32 v[18:19], s[38:39], s13, v18, 0
	v_add3_u32 v19, v19, v24, v25
	v_mul_lo_u32 v24, s8, v21
	v_mul_lo_u32 v25, s9, v20
	v_mad_u64_u32 v[20:21], s[38:39], s8, v20, 0
	v_add3_u32 v21, v21, v24, v25
	v_lshl_add_u64 v[20:21], v[20:21], 2, v[14:15]
	v_lshl_add_u64 v[18:19], v[18:19], 2, v[14:15]
	global_load_dword v104, v[20:21], off
	global_load_dword v105, v[18:19], off
	v_mad_u64_u32 v[116:117], s[38:39], v22, s44, v[8:9]
	v_add_u32_e32 v17, 0x400, v17
	v_add_u32_e32 v16, 0x400, v16
	v_mad_u64_u32 v[118:119], s[38:39], v23, s44, v[8:9]
	v_ashrrev_i32_e32 v23, 6, v17
	v_ashrrev_i32_e32 v22, 6, v16
	v_add_u32_e32 v18, s11, v23
	v_add_u32_e32 v20, s12, v22
	v_ashrrev_i32_e32 v19, 31, v18
	v_ashrrev_i32_e32 v21, 31, v20
	v_mul_lo_u32 v24, s13, v19
	v_mul_lo_u32 v25, s37, v18
	v_mad_u64_u32 v[18:19], s[38:39], s13, v18, 0
	v_add3_u32 v19, v19, v24, v25
	v_mul_lo_u32 v24, s8, v21
	v_mul_lo_u32 v25, s9, v20
	v_mad_u64_u32 v[20:21], s[38:39], s8, v20, 0
	v_add3_u32 v21, v21, v24, v25
	v_lshl_add_u64 v[20:21], v[20:21], 2, v[14:15]
	v_lshl_add_u64 v[18:19], v[18:19], 2, v[14:15]
	global_load_dword v106, v[20:21], off
	global_load_dword v107, v[18:19], off
	v_mad_u64_u32 v[120:121], s[38:39], v22, s44, v[8:9]
	v_add_u32_e32 v17, 0x400, v17
	v_add_u32_e32 v16, 0x400, v16
	v_mad_u64_u32 v[122:123], s[38:39], v23, s44, v[8:9]
	s_waitcnt vmcnt(0)
	ds_write_b32 v108, v100
	ds_write_b32 v110, v101
	ds_write_b32 v112, v102
	ds_write_b32 v114, v103
	ds_write_b32 v116, v104
	ds_write_b32 v118, v105
	ds_write_b32 v120, v106
	ds_write_b32 v122, v107
	s_or_b64 exec, exec, s[34:35]
	s_orn2_b64 s[34:35], s[4:5], exec
	v_mov_b32_e32 v0, v34
